# post phase: one 4-token group per loop trip (four waves share a tile) so the last round of the static schedule is a quarter tile
# speedup vs baseline: 1.0043x; 1.0043x over previous
; __device__ __forceinline__ int tid_of(int wv) { int t = wv * 64 + lane_id(); asm volatile("" : "+v"(t)); return t; }
; __device__ __forceinline__ int bidx() { int t = blockIdx.x; asm volatile("" : "+s"(t)); return t; }
; __device__ __forceinline__ void phase_post(const PP& p, int l) {
;     const int lane = tid_of(p.wv) & 63, gw = bidx() * 8 + (tid_of(p.wv) >> 6), nw = gridDim.x * 8, tk = lane >> 4, c4 = lane & 15;
;     const bf16_t* Z = (const bf16_t*)(p.ws + OFF_Z);
;     const bf16_t* YO = (const bf16_t*)(p.ws + OFF_YO);
;     const float* BC = (const float*)(p.ws + OFF_BC);
;     const bf16_t* Y5 = (const bf16_t*)(p.ws + OFF_Y5);
;     bf16_t* MIX = (bf16_t*)(p.ws + OFF_H);
;     const float* mu = p.in[I_MU] + l * 1408;
;     const size_t YS = (size_t)MROWS * 384;
;     for (int it3 = gw; it3 < 2 * (MROWS / 16); it3 += nw) {
;       const int item = it3 >> 1, part = 1 + (((it3 / nw) + it3) & 1);
;       if (part == 1) {
; #pragma unroll 1
;         for (int tg = 0; tg < 4; ++tg) {
;             const int row = item * 16 + tg * 4 + tk, b = row / TT, j = row - b * TT;
;     ...
; #pragma unroll 1
;         for (int tg = 0; tg < 4; ++tg) {
;             const int row = item * 16 + tg * 4 + tk, b = row / TT, j = row - b * TT;
.LBB0_1007:
	s_or_b64 exec, exec, s[0:1]
	v_readlane_b32 s0, v254, 17
	s_waitcnt lgkmcnt(0)
	v_mov_b32_e32 v2, v162
	v_readlane_b32 s4, v252, 0
	v_mov_b32_e32 v1, v162
	v_mov_b32_e32 v4, s0
	s_barrier
	ds_read_b64 v[4:5], v4
	v_ashrrev_i32_e32 v3, 6, v1
	v_and_b32_e32 v35, 3, v3
	v_lshrrev_b32_e32 v3, 2, v3
	v_readfirstlane_b32 s99, v35
	v_lshl_add_u32 v1, s4, 1, v3
	s_add_i32 s98, s99, 1
	s_movk_i32 s0, 0x1080
	v_cmp_gt_i32_e32 vcc, s0, v1
	s_waitcnt lgkmcnt(0)
	v_readfirstlane_b32 s5, v5
	v_readfirstlane_b32 s6, v4
	s_and_saveexec_b64 s[0:1], vcc
	s_cbranch_execz .LBB0_1028
	v_lshlrev_b32_e32 v4, 2, v2
	v_lshrrev_b32_e32 v5, 1, v2
	v_and_b32_e32 v14, 60, v4
	v_and_b32_e32 v5, 6, v5
	v_mul_u32_u24_e32 v6, 0x84000, v5
	v_or_b32_e32 v5, 64, v14
	v_lshrrev_b32_e32 v5, 3, v5
	v_and_b32_e32 v5, 14, v5
	v_readlane_b32 s22, v254, 58
	v_mul_u32_u24_e32 v8, 0x84000, v5
	v_or_b32_e32 v5, 0x80, v14
	v_readlane_b32 s23, v254, 59
	v_lshrrev_b32_e32 v5, 3, v5
	s_lshl_b32 s12, s22, 6
	v_and_b32_e32 v5, 22, v5
	v_lshlrev_b32_e32 v3, 3, v3
	v_readlane_b32 s22, v254, 51
	v_bfe_u32 v15, v2, 4, 2
	v_mul_u32_u24_e32 v10, 0x84000, v5
	v_or_b32_e32 v5, 0xc0, v14
	v_and_b32_e32 v2, 15, v2
	s_waitcnt vmcnt(3)
	v_lshl_add_u32 v66, s4, 4, v3
	v_readlane_b32 s23, v254, 52
	s_add_u32 s4, s6, s22
	v_lshrrev_b32_e32 v5, 3, v5
	v_lshlrev_b32_e32 v16, 3, v2
	v_lshlrev_b32_e32 v2, 4, v2
	v_mov_b32_e32 v3, v0
	s_addc_u32 s5, s5, s23
	v_and_b32_e32 v5, 30, v5
	v_lshl_add_u64 v[20:21], s[4:5], 0, v[2:3]
	v_readlane_b32 s4, v254, 49
	v_and_b32_e32 v4, 12, v4
	v_mul_u32_u24_e32 v12, 0x84000, v5
	v_mov_b32_e32 v17, v0
	v_readlane_b32 s5, v254, 50
	v_lshl_add_u64 v[18:19], s[14:15], 0, v[16:17]
	s_lshl_b64 s[22:23], s[12:13], 2
	v_lshl_add_u64 v[22:23], s[4:5], 0, v[2:3]
	s_mov_b64 s[4:5], 0
	v_lshlrev_b32_e32 v67, 2, v14
	v_lshlrev_b32_e32 v24, 1, v4
	v_lshlrev_b32_e32 v26, 1, v6
	v_lshlrev_b32_e32 v28, 1, v8
	v_lshlrev_b32_e32 v30, 1, v10
	v_lshlrev_b32_e32 v32, 1, v12
	s_branch .LBB0_1010
.LBB0_1009:
	s_or_b64 exec, exec, s[24:25]
	v_readlane_b32 s6, v254, 7
	v_readlane_b32 s7, v254, 8
	s_lshr_b32 s6, s6, 2
	v_add_u32_e32 v1, s6, v1
	s_movk_i32 s6, 0x107f
	v_cmp_lt_i32_e32 vcc, s6, v1
	v_readlane_b32 s6, v254, 1
	s_or_b64 s[4:5], vcc, s[4:5]
	s_lshr_b32 s6, s6, 2
	v_add_u32_e32 v66, s6, v66
	s_andn2_b64 exec, exec, s[4:5]
	s_cbranch_execz .LBB0_1028
.LBB0_1010:
	v_sub_u32_e32 v3, 0, v1
	v_ashrrev_i32_e32 v2, 31, v1
	v_readlane_b32 s6, v253, 59
	v_max_i32_e32 v3, v1, v3
	v_mul_hi_u32 v4, v3, v170
	v_xor_b32_e32 v2, s6, v2
	v_readlane_b32 s6, v253, 58
	v_and_or_b32 v34, v66, -16, v15
	v_lshl_add_u32 v34, s99, 2, v34
	s_nop 0
	v_mul_lo_u32 v5, v4, s6
	v_sub_u32_e32 v3, v3, v5
	v_add_u32_e32 v5, 1, v4
	v_cmp_le_u32_e32 vcc, s6, v3
	s_nop 1
	v_cndmask_b32_e32 v4, v4, v5, vcc
	v_subrev_u32_e32 v5, s6, v3
	v_cndmask_b32_e32 v3, v3, v5, vcc
	v_add_u32_e32 v5, 1, v4
	v_cmp_le_u32_e32 vcc, s6, v3
	s_nop 1
	v_cndmask_b32_e32 v3, v4, v5, vcc
	v_xor_b32_e32 v3, v3, v2
	v_sub_u32_e32 v2, v3, v2
	v_add_u32_e32 v2, v2, v1
	v_and_b32_e32 v2, 1, v2
	v_cmp_eq_u32_e32 vcc, 1, v2
	v_lshlrev_b32_e32 v2, 3, v1
	v_and_or_b32 v68, v2, -16, v15
	s_and_saveexec_b64 s[6:7], vcc
	s_xor_b64 s[24:25], exec, s[6:7]
	s_cbranch_execz .LBB0_1015
	v_readlane_b32 s6, v254, 35
	s_nop 1
	v_mov_b32_e32 v2, s6
	ds_read_b64 v[6:7], v2
	s_mov_b32 s6, s99

; __device__ __forceinline__ f32x4 unpk4(u32x2 v) { return (f32x4){bflo(v.x), bfhi(v.x), bflo(v.y), bfhi(v.y)}; }
; __device__ __forceinline__ void phase_post(const PP& p, int l) {
;     ...
; #pragma unroll 3
;             for (int h = 0; h < 6; ++h) {
;                 const int c = h * 64 + 4 * c4;
;                 const f32x4 o = unpk4(*(const u32x2*)(YO + 2 * YS + (size_t)row * 384 + c)) + unpk4(*(const u32x2*)(YO + 3 * YS + (size_t)row * 384 + c));
;                 const float rs = __builtin_amdgcn_rsqf(red16(o[0] * o[0] + o[1] * o[1] + o[2] * o[2] + o[3] * o[3]) * (1.f / 64.f) + 1e-6f);
;                 f32x4 gt = unpk4(*(const u32x2*)(Z + (size_t)row * ZLD + 2584 + c));
.LBB0_1013:
	v_lshl_add_u64 v[36:37], v[12:13], 0, s[26:27]
	v_add_co_u32_e32 v42, vcc, 0x16a3c000, v36
	s_mov_b32 s7, 0x7971000
	s_nop 0
	v_addc_co_u32_e32 v43, vcc, 0, v37, vcc
	v_add_co_u32_e32 v38, vcc, 0x182fc000, v36
	s_nop 1
	v_addc_co_u32_e32 v39, vcc, 0, v37, vcc
	v_lshl_add_u64 v[36:37], v[10:11], 0, s[26:27]
	v_add_co_u32_e32 v36, vcc, s7, v36
	s_nop 1
	v_addc_co_u32_e32 v37, vcc, 0, v37, vcc
	global_load_dwordx2 v[84:85], v[42:43], off
	global_load_dwordx2 v[86:87], v[38:39], off
	global_load_dwordx2 v[88:89], v[36:37], off offset:1072
	global_load_dwordx2 v[182:183], v[42:43], off offset:128
	global_load_dwordx2 v[184:185], v[38:39], off offset:128
	global_load_dwordx2 v[186:187], v[36:37], off offset:1200
	global_load_dwordx2 v[212:213], v[42:43], off offset:256
	global_load_dwordx2 v[214:215], v[38:39], off offset:256
	global_load_dwordx2 v[216:217], v[36:37], off offset:1328
	v_lshl_add_u64 v[40:41], v[8:9], 0, s[26:27]
	v_add_co_u32_e32 v40, vcc, s17, v40
	s_add_u32 s26, s26, 0x180
	s_addc_u32 s27, s27, 0
	v_addc_co_u32_e32 v41, vcc, 0, v41, vcc
	s_waitcnt vmcnt(0)
	v_lshlrev_b32_e32 v90, 16, v84
	v_lshlrev_b32_e32 v188, 16, v182
	v_lshlrev_b32_e32 v218, 16, v212
	v_and_b32_e32 v91, 0xffff0000, v84
	v_and_b32_e32 v189, 0xffff0000, v182
	v_and_b32_e32 v219, 0xffff0000, v212
	v_lshlrev_b32_e32 v92, 16, v85
	v_lshlrev_b32_e32 v190, 16, v183
	v_lshlrev_b32_e32 v220, 16, v213
	v_and_b32_e32 v93, 0xffff0000, v85
	v_and_b32_e32 v191, 0xffff0000, v183
	v_and_b32_e32 v221, 0xffff0000, v213
	v_lshlrev_b32_e32 v94, 16, v86
	v_lshlrev_b32_e32 v192, 16, v184
	v_lshlrev_b32_e32 v222, 16, v214
	v_and_b32_e32 v95, 0xffff0000, v86
	v_and_b32_e32 v193, 0xffff0000, v184
	v_and_b32_e32 v223, 0xffff0000, v214
	v_lshlrev_b32_e32 v96, 16, v87
	v_lshlrev_b32_e32 v194, 16, v185
	v_lshlrev_b32_e32 v224, 16, v215
	v_and_b32_e32 v97, 0xffff0000, v87
	v_and_b32_e32 v195, 0xffff0000, v185
	v_and_b32_e32 v225, 0xffff0000, v215
	v_pk_add_f32 v[90:91], v[90:91], v[94:95]
	v_pk_add_f32 v[188:189], v[188:189], v[192:193]
	v_pk_add_f32 v[218:219], v[218:219], v[222:223]
	v_pk_add_f32 v[92:93], v[92:93], v[96:97]
	v_pk_add_f32 v[190:191], v[190:191], v[194:195]
	v_pk_add_f32 v[220:221], v[220:221], v[224:225]
	v_pk_mul_f32 v[98:99], v[90:91], v[90:91]
	v_pk_mul_f32 v[196:197], v[188:189], v[188:189]
	v_pk_mul_f32 v[226:227], v[218:219], v[218:219]
	v_pk_mul_f32 v[100:101], v[92:93], v[92:93]
	v_pk_mul_f32 v[198:199], v[190:191], v[190:191]
	v_pk_mul_f32 v[228:229], v[220:221], v[220:221]
	v_add_f32_e32 v110, v98, v99
	v_add_f32_e32 v208, v196, v197
	v_add_f32_e32 v238, v226, v227
	v_add_f32_e32 v110, v100, v110
	v_add_f32_e32 v208, v198, v208
	v_add_f32_e32 v238, v228, v238
	v_add_f32_e32 v110, v101, v110
	v_add_f32_e32 v208, v199, v208
	v_add_f32_e32 v238, v229, v238
	v_lshlrev_b32_e32 v102, 16, v88
	v_lshlrev_b32_e32 v200, 16, v186
	v_lshlrev_b32_e32 v230, 16, v216
	v_and_b32_e32 v103, 0xffff0000, v88
	v_and_b32_e32 v201, 0xffff0000, v186
	v_and_b32_e32 v231, 0xffff0000, v216
	v_add_f32_dpp v110, v110, v110 quad_perm:[1,0,3,2] row_mask:0xf bank_mask:0xf bound_ctrl:1
	v_add_f32_dpp v208, v208, v208 quad_perm:[1,0,3,2] row_mask:0xf bank_mask:0xf bound_ctrl:1
	v_add_f32_dpp v238, v238, v238 quad_perm:[1,0,3,2] row_mask:0xf bank_mask:0xf bound_ctrl:1
	v_add_f32_dpp v110, v110, v110 quad_perm:[2,3,0,1] row_mask:0xf bank_mask:0xf bound_ctrl:1
	v_add_f32_dpp v208, v208, v208 quad_perm:[2,3,0,1] row_mask:0xf bank_mask:0xf bound_ctrl:1
	v_add_f32_dpp v238, v238, v238 quad_perm:[2,3,0,1] row_mask:0xf bank_mask:0xf bound_ctrl:1
	v_add_f32_dpp v110, v110, v110 row_half_mirror row_mask:0xf bank_mask:0xf bound_ctrl:1
	v_add_f32_dpp v208, v208, v208 row_half_mirror row_mask:0xf bank_mask:0xf bound_ctrl:1
	v_add_f32_dpp v238, v238, v238 row_half_mirror row_mask:0xf bank_mask:0xf bound_ctrl:1
	v_add_f32_dpp v110, v110, v110 row_ror:8 row_mask:0xf bank_mask:0xf bound_ctrl:1
	v_add_f32_dpp v208, v208, v208 row_ror:8 row_mask:0xf bank_mask:0xf bound_ctrl:1
	v_add_f32_dpp v238, v238, v238 row_ror:8 row_mask:0xf bank_mask:0xf bound_ctrl:1
	v_fmamk_f32 v110, v110, 0x3c800000, v171
	v_fmamk_f32 v208, v208, 0x3c800000, v171
	v_fmamk_f32 v238, v238, 0x3c800000, v171
	v_rsq_f32_e32 v112, v110
	v_rsq_f32_e32 v210, v208
	v_rsq_f32_e32 v240, v238
	v_lshlrev_b32_e32 v104, 16, v89
	v_lshlrev_b32_e32 v202, 16, v187
	v_lshlrev_b32_e32 v232, 16, v217
	v_and_b32_e32 v105, 0xffff0000, v89
	v_and_b32_e32 v203, 0xffff0000, v187
	v_and_b32_e32 v233, 0xffff0000, v217
	v_mul_f32_e32 v106, 0xbfb8aa3b, v102
	v_mul_f32_e32 v204, 0xbfb8aa3b, v200
	v_mul_f32_e32 v234, 0xbfb8aa3b, v230
	v_mul_f32_e32 v107, 0xbfb8aa3b, v103
	v_mul_f32_e32 v205, 0xbfb8aa3b, v201
	v_mul_f32_e32 v235, 0xbfb8aa3b, v231
	v_mul_f32_e32 v108, 0xbfb8aa3b, v104
	v_mul_f32_e32 v206, 0xbfb8aa3b, v202
	v_mul_f32_e32 v236, 0xbfb8aa3b, v232
; __device__ __forceinline__ f32x4 unpk4(u32x2 v) { return (f32x4){bflo(v.x), bfhi(v.x), bflo(v.y), bfhi(v.y)}; }
; __device__ __forceinline__ u32x2 pk4(f32x4 v) { u32x2 r; r.x = pk2(v[0], v[1]); r.y = pk2(v[2], v[3]); return r; }
; __device__ __forceinline__ float siluf_(float x) { return x * rcpf_(1.f + __expf(-x)); }
; __device__ __forceinline__ int s5pos(int j) { if (j < CTX) return j; const int tok = j - CTX; return CTX + (tok & 63) * 128 + (tok >> 6); }
; __device__ __forceinline__ void phase_post(const PP& p, int l) {
;     ...
;         for (int tg = 0; tg < 4; ++tg) {
;             const int row = item * 16 + tg * 4 + tk, b = row / TT, j = row - b * TT;
;     ...
;         for (int tg = 0; tg < 4; ++tg) {
;             const int row = item * 16 + tg * 4 + tk, b = row / TT, j = row - b * TT;
;             const f32x4 gn = *(const f32x4*)(p.in[I_GNG] + l * 64 + 4 * c4);
; #pragma unroll 3
;             for (int h = 0; h < 6; ++h) {
;                 const int c = h * 64 + 4 * c4;
;                 const f32x4 o = unpk4(*(const u32x2*)(YO + 2 * YS + (size_t)row * 384 + c)) + unpk4(*(const u32x2*)(YO + 3 * YS + (size_t)row * 384 + c));
;                 const float rs = __builtin_amdgcn_rsqf(red16(o[0] * o[0] + o[1] * o[1] + o[2] * o[2] + o[3] * o[3]) * (1.f / 64.f) + 1e-6f);
;                 f32x4 gt = unpk4(*(const u32x2*)(Z + (size_t)row * ZLD + 2584 + c));
; #pragma unroll
;                 for (int i = 0; i < 4; ++i) gt[i] = siluf_(gt[i]);
;                 *(u32x2*)(MIX + (size_t)row * DM + 384 + c) = pk4(o * rs * gn * gt);
;             }
;             const int n = s5pos(j), R = b * NCH + (n >> 5), t = n & 31;
;             const size_t GS5 = (size_t)GROWS * 512;
; #pragma unroll
;             for (int e = 0; e < 4; ++e) {
;                 const int ch = e * 64 + 4 * c4, nt = ch >> 4, hh = ch & 15;
;                 *(u32x2*)(MIX + (size_t)row * DM + 768 + ch) = *(const u32x2*)(Y5 + (size_t)(nt * 2) * GS5 + (size_t)R * 512 + t * 16 + hh);
;             }
;         }
	v_mul_f32_e32 v109, 0xbfb8aa3b, v105
	v_mul_f32_e32 v207, 0xbfb8aa3b, v203
	v_mul_f32_e32 v237, 0xbfb8aa3b, v233
	v_exp_f32_e32 v106, v106
	v_exp_f32_e32 v204, v204
	v_exp_f32_e32 v234, v234
	v_exp_f32_e32 v107, v107
	v_exp_f32_e32 v205, v205
	v_exp_f32_e32 v235, v235
	v_exp_f32_e32 v108, v108
	v_exp_f32_e32 v206, v206
	v_exp_f32_e32 v236, v236
	v_exp_f32_e32 v109, v109
	v_exp_f32_e32 v207, v207
	v_exp_f32_e32 v237, v237
	v_add_f32_e32 v106, 1.0, v106
	v_add_f32_e32 v204, 1.0, v204
	v_add_f32_e32 v234, 1.0, v234
	v_add_f32_e32 v107, 1.0, v107
	v_add_f32_e32 v205, 1.0, v205
	v_add_f32_e32 v235, 1.0, v235
	v_add_f32_e32 v108, 1.0, v108
	v_add_f32_e32 v206, 1.0, v206
	v_add_f32_e32 v236, 1.0, v236
	v_add_f32_e32 v109, 1.0, v109
	v_add_f32_e32 v207, 1.0, v207
	v_add_f32_e32 v237, 1.0, v237
	v_rcp_f32_e32 v106, v106
	v_rcp_f32_e32 v204, v204
	v_rcp_f32_e32 v234, v234
	v_rcp_f32_e32 v107, v107
	v_rcp_f32_e32 v205, v205
	v_rcp_f32_e32 v235, v235
	v_rcp_f32_e32 v108, v108
	v_rcp_f32_e32 v206, v206
	v_rcp_f32_e32 v236, v236
	v_rcp_f32_e32 v109, v109
	v_rcp_f32_e32 v207, v207
	v_rcp_f32_e32 v237, v237
	v_pk_mul_f32 v[90:91], v[90:91], v[112:113] op_sel_hi:[1,0]
	v_pk_mul_f32 v[188:189], v[188:189], v[210:211] op_sel_hi:[1,0]
	v_pk_mul_f32 v[218:219], v[218:219], v[240:241] op_sel_hi:[1,0]
	v_pk_mul_f32 v[92:93], v[92:93], v[112:113] op_sel_hi:[1,0]
	v_pk_mul_f32 v[190:191], v[190:191], v[210:211] op_sel_hi:[1,0]
	v_pk_mul_f32 v[220:221], v[220:221], v[240:241] op_sel_hi:[1,0]
	v_pk_mul_f32 v[102:103], v[106:107], v[102:103]
	v_pk_mul_f32 v[200:201], v[204:205], v[200:201]
	v_pk_mul_f32 v[230:231], v[234:235], v[230:231]
	v_pk_mul_f32 v[104:105], v[108:109], v[104:105]
	v_pk_mul_f32 v[202:203], v[206:207], v[202:203]
	v_pk_mul_f32 v[232:233], v[236:237], v[232:233]
	v_pk_mul_f32 v[90:91], v[2:3], v[90:91]
	v_pk_mul_f32 v[188:189], v[2:3], v[188:189]
	v_pk_mul_f32 v[218:219], v[2:3], v[218:219]
	v_pk_mul_f32 v[92:93], v[4:5], v[92:93]
	v_pk_mul_f32 v[190:191], v[4:5], v[190:191]
	v_pk_mul_f32 v[220:221], v[4:5], v[220:221]
	v_pk_mul_f32 v[90:91], v[102:103], v[90:91]
	v_pk_mul_f32 v[188:189], v[200:201], v[188:189]
	v_pk_mul_f32 v[218:219], v[230:231], v[218:219]
	v_pk_mul_f32 v[92:93], v[104:105], v[92:93]
	v_pk_mul_f32 v[190:191], v[202:203], v[190:191]
	v_pk_mul_f32 v[220:221], v[232:233], v[220:221]
	v_cvt_pk_bf16_f32 v90, v90, v91
	v_cvt_pk_bf16_f32 v188, v188, v189
	v_cvt_pk_bf16_f32 v218, v218, v219
	v_cvt_pk_bf16_f32 v91, v92, v93
	v_cvt_pk_bf16_f32 v189, v190, v191
	v_cvt_pk_bf16_f32 v219, v220, v221
	global_store_dwordx2 v[40:41], v[90:91], off offset:768
	global_store_dwordx2 v[40:41], v[188:189], off offset:896
	global_store_dwordx2 v[40:41], v[218:219], off offset:1024
	s_cmpk_eq_i32 s26, 0x300
	s_cbranch_scc0 .LBB0_1013
	v_lshl_add_u32 v2, s6, 2, v68
	v_mul_hi_i32 v3, v2, s30
	v_lshrrev_b32_e32 v4, 31, v3
	v_ashrrev_i32_e32 v3, 11, v3
	v_add_u32_e32 v8, v3, v4
	v_ashrrev_i32_e32 v3, 31, v2
	v_lshlrev_b64 v[4:5], 11, v[2:3]
	v_mad_i32_i24 v3, v8, s51, v2
	v_add_u32_e32 v9, 0xffffff00, v3
	v_lshlrev_b32_e32 v2, 7, v2
	v_and_b32_e32 v2, 0x1f80, v2
	v_lshrrev_b32_e32 v9, 6, v9
	v_cmp_gt_i32_e32 vcc, s33, v3
	v_add3_u32 v2, v2, v9, s33
	s_movk_i32 s7, 0x108
	v_cndmask_b32_e32 v9, v2, v3, vcc
	v_ashrrev_i32_e32 v2, 5, v9
	v_mad_i32_i24 v2, v8, s7, v2
	v_ashrrev_i32_e32 v3, 31, v2
	v_lshlrev_b64 v[2:3], 10, v[2:3]
	v_lshlrev_b32_e32 v8, 5, v9
	v_lshl_add_u64 v[2:3], s[18:19], 0, v[2:3]
	v_and_b32_e32 v8, 0x3e0, v8
	v_mov_b32_e32 v9, v0
	v_lshl_add_u64 v[2:3], v[2:3], 0, v[8:9]
	v_mov_b32_e32 v25, v0
	v_lshl_add_u64 v[2:3], v[2:3], 0, v[24:25]
	v_mov_b32_e32 v27, v0
	v_lshl_add_u64 v[84:85], v[2:3], 0, v[26:27]
	v_mov_b32_e32 v29, v0
	v_mov_b32_e32 v31, v0
	v_mov_b32_e32 v33, v0
	v_lshl_add_u64 v[86:87], v[2:3], 0, v[28:29]
	v_lshl_add_u64 v[88:89], v[2:3], 0, v[30:31]
	v_lshl_add_u64 v[90:91], v[2:3], 0, v[32:33]
	global_load_dwordx2 v[92:93], v[84:85], off
	global_load_dwordx2 v[94:95], v[86:87], off
	global_load_dwordx2 v[96:97], v[88:89], off
	global_load_dwordx2 v[98:99], v[90:91], off
	v_lshl_add_u64 v[4:5], s[10:11], 0, v[4:5]
	v_lshlrev_b32_e32 v10, 1, v14
	v_mov_b32_e32 v11, v0
	v_lshl_add_u64 v[4:5], v[4:5], 0, v[10:11]
	s_add_i32 s6, s6, 1
	v_add_u32_e32 v34, 4, v34
	s_waitcnt vmcnt(0)
	global_store_dwordx2 v[4:5], v[92:93], off offset:1536
	global_store_dwordx2 v[4:5], v[94:95], off offset:1664
	global_store_dwordx2 v[4:5], v[96:97], off offset:1792
	global_store_dwordx2 v[4:5], v[98:99], off offset:1920
	s_cmp_eq_u32 s6, s98
	s_cbranch_scc0 .LBB0_1012
.LBB0_1015:
	s_andn2_saveexec_b64 s[24:25], s[24:25]
	s_cbranch_execz .LBB0_1009
	v_readlane_b32 s6, v254, 36
	s_nop 1
	v_mov_b32_e32 v2, s6
	ds_read_b128 v[2:5], v2
	s_mov_b32 s6, s99
	s_branch .LBB0_1018
.LBB0_1017:
	s_add_i32 s6, s6, 1
	s_cmp_eq_u32 s6, s98
	v_add_u32_e32 v34, 4, v34
	s_cbranch_scc1 .LBB0_1009
